# weight transposes of the prep phase moved onto the 64 workgroups that have no phase-0 GEMV slice (stride-64 item loop)
# baseline (speedup 1.0000x reference)
.LBB0_30:
	s_or_b64 exec, exec, s[6:7]
	s_load_dwordx4 s[68:71], s[0:1], 0x0
	v_readfirstlane_b32 s65, v170
	v_and_b32_e32 v222, 63, v170
	v_lshlrev_b32_e32 v229, 4, v222
	s_lshr_b32 s65, s65, 6
	s_lshl_b32 s66, s2, 3
	s_add_i32 s66, s66, s65
	s_lshl_b32 s67, s66, 12
	s_waitcnt lgkmcnt(0)
	s_add_u32 s60, s68, s67
	s_addc_u32 s61, s69, 0
	global_load_dwordx4 v[96:99], v229, s[60:61] nt
	global_load_dwordx4 v[100:103], v229, s[60:61] offset:1024 nt
	global_load_dwordx4 v[104:107], v229, s[60:61] offset:2048 nt
	global_load_dwordx4 v[108:111], v229, s[60:61] offset:3072 nt
	s_add_u32 s60, s60, 0x800000
	s_addc_u32 s61, s61, 0
	global_load_dwordx4 v[112:115], v229, s[60:61] nt
	global_load_dwordx4 v[116:119], v229, s[60:61] offset:1024 nt
	global_load_dwordx4 v[120:123], v229, s[60:61] offset:2048 nt
	global_load_dwordx4 v[124:127], v229, s[60:61] offset:3072 nt
	s_add_u32 s60, s70, s67
	s_addc_u32 s61, s71, 0
	global_load_dwordx4 v[136:139], v229, s[60:61] nt
	global_load_dwordx4 v[140:143], v229, s[60:61] offset:1024 nt
	global_load_dwordx4 v[144:147], v229, s[60:61] offset:2048 nt
	global_load_dwordx4 v[148:151], v229, s[60:61] offset:3072 nt
	s_add_u32 s60, s60, 0x800000
	s_addc_u32 s61, s61, 0
	global_load_dwordx4 v[152:155], v229, s[60:61] nt
	global_load_dwordx4 v[156:159], v229, s[60:61] offset:1024 nt
	global_load_dwordx4 v[160:163], v229, s[60:61] offset:2048 nt
	global_load_dwordx4 v[164:167], v229, s[60:61] offset:3072 nt
	s_add_u32 s60, s60, 0x800000
	s_addc_u32 s61, s61, 0
	global_load_dwordx4 v[178:181], v229, s[60:61] nt
	global_load_dwordx4 v[182:185], v229, s[60:61] offset:1024 nt
	global_load_dwordx4 v[186:189], v229, s[60:61] offset:2048 nt
	global_load_dwordx4 v[190:193], v229, s[60:61] offset:3072 nt
	s_add_u32 s60, s60, 0x800000
	s_addc_u32 s61, s61, 0
	global_load_dwordx4 v[194:197], v229, s[60:61] nt
	global_load_dwordx4 v[198:201], v229, s[60:61] offset:1024 nt
	global_load_dwordx4 v[202:205], v229, s[60:61] offset:2048 nt
	global_load_dwordx4 v[206:209], v229, s[60:61] offset:3072 nt
	s_mov_b64 s[4:5], s[0:1]
	v_mov_b32_e32 v0, v170
	s_cmpk_lt_i32 s2, 0xc0
	s_cbranch_scc1 .LBB0_71
	s_load_dwordx2 s[6:7], s[4:5], 0xe8
	v_add_u32_e32 v4, 0x200, v0
	v_ashrrev_i32_e32 v11, 6, v4
	v_add_u32_e32 v4, 0x400, v0
	v_ashrrev_i32_e32 v12, 6, v4
	v_add_u32_e32 v4, 0x600, v0
	v_ashrrev_i32_e32 v13, 6, v4
	v_add_u32_e32 v4, 0x800, v0
	s_waitcnt lgkmcnt(0)
	s_add_u32 s8, s6, 0x780000
	v_ashrrev_i32_e32 v14, 6, v4
	v_add_u32_e32 v4, 0xa00, v0
	s_addc_u32 s9, s7, 0
	v_ashrrev_i32_e32 v15, 6, v4
	v_add_u32_e32 v4, 0xc00, v0
	s_add_u32 s3, s6, 0xe3c000
	v_ashrrev_i32_e32 v16, 6, v4
	v_add_u32_e32 v4, 0xe00, v0
	s_addc_u32 s30, s7, 0
	v_ashrrev_i32_e32 v17, 6, v4
	v_bfe_u32 v4, v0, 4, 2
	v_lshlrev_b32_e32 v5, 4, v0
	v_lshlrev_b32_e32 v3, 3, v0
	s_add_u32 s10, s6, 0xdbc000
	v_mul_u32_u24_e32 v4, 0x4100, v4
	v_and_b32_e32 v5, 0xf0, v5
	s_addc_u32 s11, s7, 0
	v_add3_u32 v5, 0, v4, v5
	v_and_b32_e32 v4, 56, v3
	s_add_u32 s12, s6, 0xbbc000
	v_ashrrev_i32_e32 v18, 3, v0
	v_mul_u32_u24_e32 v3, 0x41, v4
	v_ashrrev_i32_e32 v10, 6, v0
	v_lshlrev_b32_e32 v1, 2, v0
	s_addc_u32 s13, s7, 0
	s_movk_i32 s16, 0x104
	v_lshlrev_b32_e32 v20, 2, v18
	v_lshlrev_b32_e32 v3, 2, v3
	v_and_b32_e32 v2, 0xfc, v1
	s_add_u32 s14, s6, 0x7bc000
	v_mul_lo_u32 v6, v10, s16
	v_mul_lo_u32 v7, v11, s16
	v_mul_lo_u32 v8, v12, s16
	v_mul_lo_u32 v9, v13, s16
	v_mul_lo_u32 v26, v14, s16
	v_mul_lo_u32 v27, v15, s16
	v_mul_lo_u32 v28, v16, s16
	v_mul_lo_u32 v29, v17, s16
	v_add3_u32 v19, 0, v20, v3
	v_add3_u32 v20, 0, v3, v20
	s_addc_u32 s15, s7, 0
	v_mov_b32_e32 v1, 0
	s_mov_b32 s17, 0
	v_lshl_add_u32 v21, s2, 9, v0
	s_lshl_b32 s31, s42, 9
	v_lshlrev_b32_e32 v2, 2, v2
	v_add_u32_e32 v22, v5, v6
	v_add_u32_e32 v23, v5, v7
	v_add_u32_e32 v24, v5, v8
	v_add_u32_e32 v25, v5, v9
	v_add_u32_e32 v26, v5, v26
	v_add_u32_e32 v27, v5, v27
	v_add_u32_e32 v28, v5, v28
	v_add_u32_e32 v29, v5, v29
	v_lshlrev_b32_e32 v4, 1, v4
	s_mov_b32 s34, 0x88888889
	s_movk_i32 s35, 0x8800
	s_mov_b32 s36, 0x2aaaaaab
	s_movk_i32 s37, 0x6000
	s_movk_i32 s40, 0x3ff
	v_add_u32_e32 v30, 0x400, v19
	v_add_u32_e32 v31, 0x400, v20
	v_add_u32_e32 v32, 0x4000, v19
	v_add_u32_e32 v33, 0x4200, v20
	v_add_u32_e32 v34, 0x4400, v19
	v_add_u32_e32 v35, 0x4600, v20
	v_add_u32_e32 v36, 0x8200, v19
	v_add_u32_e32 v37, 0x8200, v20
	v_add_u32_e32 v38, 0x8600, v19
	v_add_u32_e32 v39, 0x8600, v20
	v_add_u32_e32 v40, 0xc200, v19
	v_add_u32_e32 v41, 0xc400, v20
	v_add_u32_e32 v42, 0xc600, v19
	v_add_u32_e32 v43, 0xc800, v20
	s_add_i32 s41, s2, 0xffffffb8
	s_branch .LBB0_34

.LBB0_33:
	s_add_i32 s41, s41, 64
	s_cmpk_lt_i32 s41, 0x158
	v_add_u32_e32 v21, s31, v21
	s_cbranch_scc0 .LBB0_71
